# per-head queues for prompt diff and prompt FoX (blockIdx-affine), P3 sample-row normalisation loads issued together; P3 fused epilogue back to baseline form
# baseline (speedup 1.0000x reference)
; #define LAS __attribute__((address_space(3)))
; template <int KIND>
; __device__ __forceinline__ void attn_queue(const AttnCtx& C, unsigned* head, int nunits, LAS unsigned char* lds) {
;     volatile LAS unsigned* slot = (volatile LAS unsigned*)(lds + AL_MISC);
;     if constexpr (KIND == 0) tuned::fox_tables(C, lds);
;     for (;;) {
;         __syncthreads();
;         if (threadIdx.x == 0) slot[0] = __hip_atomic_fetch_add(head, 1u, __ATOMIC_RELAXED, __HIP_MEMORY_SCOPE_AGENT);
;         __syncthreads();
;         const unsigned u = slot[0];
;         if (u >= (unsigned)nunits) break;
.LBB0_809:
	s_barrier
	s_mov_b64 s[2:3], exec
	v_readlane_b32 s0, v253, 26
	v_readlane_b32 s1, v253, 27
	s_and_b64 s[0:1], s[2:3], s[0:1]
	s_mov_b64 exec, s[0:1]
	s_cbranch_execz .LBB0_813
	s_mov_b64 s[6:7], exec
	v_mbcnt_lo_u32_b32 v2, s6, 0
	v_mbcnt_hi_u32_b32 v2, s7, v2
	v_cmp_eq_u32_e32 vcc, 0, v2
	s_and_saveexec_b64 s[4:5], vcc
	s_cbranch_execz .LBB0_812
	v_readlane_b32 s0, v253, 2
	s_and_b32 s0, s0, 7
	s_lshl_b32 s0, s0, 8
	s_add_i32 s0, s0, 0x18800
	v_mov_b32_e32 v254, s0
	s_bcnt1_i32_b64 s0, s[6:7]
	v_mov_b32_e32 v4, s0
	global_atomic_add v4, v254, v4, s[94:95] sc0

; #define LAS __attribute__((address_space(3)))
; template <bool NOMAX>
; __device__ __forceinline__ void fox_unit(const AttnCtx& C, int u, LAS unsigned char* lds) {
;     int tid = threadIdx.x; asm volatile("" : "+v"(tid));
;     const int lane = tid & 63, r32 = lane & 31, hi = lane >> 5; const int wid = __builtin_amdgcn_readfirstlane(tid >> 6);
;     const int h = u & 7, qb = 63 - (u >> 3);
;     const int NT = 4 * qb + 4, tref = 4 * qb, q0 = 256 * qb;
;     LAS float* ckl = (LAS float*)(lds + TF_CK);
;     LAS float* wsf = (LAS float*)(lds + TF_WS) + wid * 64;
;     const LAS float* PREh = (const LAS float*)(lds + FX_PRE) + h * FX_PST; const LAS float* NRMF = (const LAS float*)(lds + FX_NRM);
;     __syncthreads();
;     const bf16* Qw = C.QF + (size_t)(q0 + wid * 32) * 512 + h * 64;
;     const bf16* Kh = C.KF + h * 64; const bf16* Vh = C.VF + h * 64;
;     const unsigned lds0 = (unsigned)(size_t)lds;
;     const bf16* ksrc = Kh + (size_t)lane * 512 + wid * 8;
;     const bf16* vsrc = Vh + (size_t)(16 * (wid & 3) + (lane >> 2)) * 512 + (wid >> 2) * 32 + (lane & 3) * 8;
;     const unsigned kdst = lds0 + TF_K + wid * 1024, vdst = lds0 + TF_V + wid * 1024;
;     ...
;     const lcp kp0 = (lcp)(lds + TF_K) + hi * 1024 + r32 * 16;
; template <int KIND>
; __device__ __forceinline__ void attn_queue(const AttnCtx& C, unsigned* head, int nunits, LAS unsigned char* lds) {
;     ...
;         const unsigned u = slot[0];
;         if (u >= (unsigned)nunits) break;
;         if (KIND == 0) {
;             bool nmx_ = false;
;             if constexpr (KIND == 0) { const int hh_ = (int)u & 7, tr_ = 4 * (63 - ((int)u >> 3)); const LAS float* pr_ = (const LAS float*)(lds + tuned::FX_PRE) + hh_ * tuned::FX_PST; const LAS float* nr_ = (const LAS float*)(lds + tuned::FX_NRM);
;                 const float g_ = (pr_[tr_] - pr_[tr_ + 4]) * LOG2E, b_ = 1.01f * sqrtf((nr_[hh_ * 2] + nr_[hh_ * 2 + 1]) * (nr_[16 + hh_ * 2] + nr_[16 + hh_ * 2 + 1]));
;                 nmx_ = __builtin_amdgcn_readfirstlane((b_ + g_ <= 100.0f) ? 1 : 0) != 0; }
;             if (nmx_) tuned::fox_unit<true>(C, (int)u, lds); else tuned::fox_unit<false>(C, (int)u, lds); } else if (KIND == 1) { if ((C.nomax >> (2 * ((int)u & 3) + (((int)u >> 2) & 1))) & 1) tuned::diff_unit<true>(C, (int)u, lds); else tuned::diff_unit<false>(C, (int)u, lds); } else { if constexpr (KIND == 3) { sample_diff2<0>(C, (int)u, lds);
.LBB0_813:
	s_or_b64 exec, exec, s[2:3]
	s_waitcnt lgkmcnt(0)
	s_barrier
	ds_read_b32 v2, v1
	s_movk_i32 s0, 0x3f
	s_mov_b64 s[2:3], -1
	s_waitcnt lgkmcnt(0)
	v_cmp_lt_u32_e32 vcc, s0, v2
	v_readfirstlane_b32 s1, v2
	s_cbranch_vccnz .LBB0_808
	v_readlane_b32 s0, v253, 2
	s_and_b32 s0, s0, 7
	v_lshlrev_b32_e32 v2, 3, v2
	s_lshl_b32 s1, s1, 3
	s_or_b32 s1, s1, s0
	v_or_b32_e32 v2, s0, v2
	s_and_b32 s86, s1, 7
	s_lshl_b32 s3, s86, 3
	s_add_i32 s3, s3, 0
	s_add_i32 s10, s3, 0x25080
	v_mov_b32_e32 v2, s10
	ds_read2_b64 v[4:7], v2 offset1:8
	s_not_b32 s2, s1
	s_mul_i32 s0, s86, 0x410
	s_add_i32 s0, s0, 0
	s_lshl_b32 s2, s2, 1
	s_add_i32 s0, s0, 0x22800
	s_and_b32 s2, s2, 0x3f0
	s_add_i32 s2, s0, s2
	s_waitcnt lgkmcnt(0)
	v_mov_b32_e32 v10, v4
	v_mov_b32_e32 v11, v6
	v_mov_b32_e32 v6, v5
	v_mov_b32_e32 v2, s2
	v_pk_add_f32 v[4:5], v[10:11], v[6:7]
	ds_read2_b32 v[8:9], v2 offset1:4
	v_mul_f32_e32 v2, v4, v5
	v_mul_f32_e32 v4, 0x4f800000, v2
	v_cmp_gt_f32_e32 vcc, s9, v2
	s_lshr_b32 s1, s1, 3
	s_xor_b32 s88, s1, 63
	v_cndmask_b32_e32 v2, v2, v4, vcc
	v_sqrt_f32_e32 v5, v2
	s_waitcnt lgkmcnt(0)
	v_sub_f32_e32 v4, v8, v9
	s_lshl_b32 s78, s88, 2
	s_lshl_b32 s11, s88, 8
	v_add_u32_e32 v6, -1, v5
	v_fma_f32 v7, -v6, v5, v2
	v_cmp_ge_f32_e64 s[2:3], 0, v7
	v_add_u32_e32 v7, 1, v5
	s_lshl_b32 s12, s86, 6
	v_cndmask_b32_e64 v6, v5, v6, s[2:3]
	v_fma_f32 v5, -v7, v5, v2
	v_cmp_lt_f32_e64 s[2:3], 0, v5
	s_lshl_b32 s1, s86, 7
	v_readlane_b32 s4, v253, 48
	v_cndmask_b32_e64 v5, v6, v7, s[2:3]
	v_mul_f32_e32 v6, 0x37800000, v5
	v_cndmask_b32_e32 v5, v5, v6, vcc
	v_cmp_class_f32_e32 vcc, v2, v211
	s_mov_b32 s2, 0x3fb8aa3b
	s_mov_b32 s3, 0x3f8147ae
	v_cndmask_b32_e32 v5, v5, v2, vcc
	v_pk_mul_f32 v[4:5], v[4:5], s[2:3]
	s_mov_b32 s2, 0x42c80000
	v_add_f32_e32 v2, v4, v5
	v_cmp_ge_f32_e32 vcc, s2, v2
	v_readlane_b32 s5, v253, 49
	s_nop 0
	v_cndmask_b32_e64 v2, 0, 1, vcc
	s_nop 0
	v_readfirstlane_b32 s2, v2
	s_and_b32 s2, s2, 1
	s_add_u32 s74, s4, s1
	s_addc_u32 s75, s5, 0
	s_cmp_eq_u32 s2, 0
	s_mov_b64 s[2:3], -1
	s_cbranch_scc0 .LBB0_949
	v_mov_b32_e32 v8, v0
	v_readlane_b32 s4, v253, 30
	v_readfirstlane_b32 s1, v8
	s_ashr_i32 s87, s1, 6
	s_lshl_b32 s8, s87, 5
	s_add_i32 s84, s8, s11
	s_ashr_i32 s85, s84, 31
	s_lshl_b64 s[2:3], s[84:85], 10
	v_readlane_b32 s5, v253, 31
	s_add_u32 s2, s4, s2
	s_addc_u32 s3, s5, s3
	s_lshl_b32 s72, s12, 1
	v_and_b32_e32 v212, 63, v8
	s_add_u32 s2, s2, s72
	s_addc_u32 s3, s3, 0
	v_lshlrev_b32_e32 v2, 10, v212
	s_lshl_b32 s4, s87, 3
	v_lshl_add_u64 v[4:5], s[74:75], 0, v[2:3]
	s_ashr_i32 s5, s4, 31
	v_lshl_add_u64 v[206:207], s[4:5], 1, v[4:5]
	s_lshl_b32 s92, s87, 10
	s_lshl_b32 s76, s88, 18
	s_barrier
	s_add_i32 s92, s92, 0
	v_lshl_add_u64 v[4:5], v[206:207], 0, s[76:77]
	s_mov_b32 s4, m0
	s_mov_b32 m0, s92
	s_nop 0
	global_load_lds_dwordx4 v[4:5], off
	s_mov_b32 m0, s4
	s_mov_b64 s[4:5], 0x10000
	v_lshl_add_u64 v[6:7], v[4:5], 0, s[4:5]
	s_add_i32 s82, s92, 0x2000
	s_mov_b32 s4, m0
	s_mov_b32 m0, s82
	s_nop 0
	global_load_lds_dwordx4 v[6:7], off
	s_mov_b32 m0, s4
	s_mov_b64 s[4:5], 0x20000
	v_lshl_add_u64 v[6:7], v[4:5], 0, s[4:5]
	s_add_i32 s83, s92, 0x4000
	s_mov_b32 s4, m0
	s_mov_b32 m0, s83
	s_nop 0
	global_load_lds_dwordx4 v[6:7], off
	s_mov_b32 m0, s4
	v_and_b32_e32 v213, 31, v8
	s_mov_b64 s[4:5], 0x30000
	v_bfe_u32 v214, v8, 5, 1
	v_lshl_add_u64 v[4:5], v[4:5], 0, s[4:5]
	v_lshlrev_b32_e32 v2, 10, v213
	s_add_i32 s93, s92, 0x6000
	s_mov_b32 s4, m0
	s_mov_b32 m0, s93
	s_nop 0
	global_load_lds_dwordx4 v[4:5], off
	s_mov_b32 m0, s4
	v_lshl_add_u64 v[6:7], s[2:3], 0, v[2:3]
	v_lshlrev_b32_e32 v4, 4, v214
	v_mov_b32_e32 v5, v3
	v_lshl_add_u64 v[6:7], v[6:7], 0, v[4:5]
	global_load_dwordx4 v[142:145], v[6:7], off
	global_load_dwordx4 v[138:141], v[6:7], off offset:32
	global_load_dwordx4 v[134:137], v[6:7], off offset:64
	global_load_dwordx4 v[130:133], v[6:7], off offset:96
	v_mov_b32_e32 v2, s10
	ds_read2_b64 v[10:13], v2 offset1:8
	s_lshl_b32 s2, s78, 2
	s_add_i32 s2, s0, s2
	v_mov_b32_e32 v6, s2
	s_lshl_b32 s76, s86, 2
	s_waitcnt lgkmcnt(0)
	v_add_f32_e32 v2, v10, v11
	v_add_f32_e32 v5, v12, v13
	v_mul_f32_e32 v2, v2, v5
	v_mul_f32_e32 v5, 0x4f800000, v2
	v_cmp_gt_f32_e32 vcc, s9, v2
	s_nop 1
	v_cndmask_b32_e32 v2, v2, v5, vcc
	v_sqrt_f32_e32 v5, v2
	s_nop 0
	v_add_u32_e32 v7, -1, v5
	v_fma_f32 v9, -v7, v5, v2
	v_cmp_ge_f32_e64 s[2:3], 0, v9
	v_add_u32_e32 v9, 1, v5
	s_nop 0
	v_cndmask_b32_e64 v7, v5, v7, s[2:3]
	v_fma_f32 v5, -v9, v5, v2
	v_cmp_lt_f32_e64 s[2:3], 0, v5
	s_nop 1
	v_cndmask_b32_e64 v5, v7, v9, s[2:3]
	s_lshl_b32 s2, s88, 5
	v_mul_f32_e32 v7, 0x37800000, v5
	s_add_i32 s2, s2, 0
	v_cndmask_b32_e32 v5, v5, v7, vcc
	v_cmp_class_f32_e32 vcc, v2, v211
	s_add_i32 s2, s2, s76
	s_add_i32 s2, s2, 0x24880
	v_cndmask_b32_e32 v2, v5, v2, vcc
	v_mul_f32_e32 v10, 0x3f8147ae, v2
	v_mov_b32_e32 v5, s2
	ds_read_b32 v2, v6
	ds_read_b32 v7, v5
	s_cmp_lt_u32 s1, 64
	v_lshlrev_b32_e32 v9, 2, v212
	s_cselect_b64 s[70:71], -1, 0
	s_cmp_gt_u32 s1, 63
	v_cmp_gt_u32_e32 vcc, s78, v9
	s_cbranch_scc1 .LBB0_835
	v_fmaak_f32 v5, 2.0, v10, 0x42400000
	v_mul_f32_e32 v6, 0xbf317218, v5
	v_mov_b32_e32 v5, 0
	s_and_saveexec_b64 s[2:3], vcc
	s_cbranch_execz .LBB0_820
	v_sub_u32_e32 v5, s78, v9
	v_lshl_add_u32 v5, v5, 2, s0
	ds_read_b32 v5, v5
	s_waitcnt lgkmcnt(0)
	v_sub_f32_e32 v5, v5, v2
	v_sub_f32_e32 v5, v7, v5
	v_cmp_le_f32_e32 vcc, v5, v6
	v_mov_b32_e32 v5, 0
	s_and_saveexec_b64 s[4:5], vcc
	v_mov_b32_e32 v5, 1
	s_or_b64 exec, exec, s[4:5]

; __global__ void __launch_bounds__(NWAVES * 64, LBW) fwd_kernel(Args A) {
;     ...
;             const float* OUTF = (const float*)(A.ws + WS_OUTF); const float* SS = (const float*)(A.ws + WS_SS);
;             int t3 = threadIdx.x; asm volatile("" : "+v"(t3));
;             const int lane = t3 & 63; const int wv3 = __builtin_amdgcn_readfirstlane(t3 >> 6);
;             const int G3 = gridDim.x, b3 = blockIdx.x; const int vcu3 = (G3 % 8 == 0) ? (b3 % 8) * (G3 / 8) + b3 / 8 : b3;
;             const int row = NP + vcu3 * NWAVES + wv3;
;             if (row < MT) {
;                 const float sv = (lane < 16) ? SS[(size_t)row * 16 + lane] : 0.f;
;                 const float rstd = 1.0f / sqrtf(wave_sum(sv) * (1.0f / D) + EPSN);
;                 const float* xr = A.x_s + (size_t)(row - NP) * D; const float* orow = OUTF + (size_t)row * D; float* yr = A.out + (size_t)row * D;
; #pragma unroll
;                 for (int j = 0; j < 4; ++j) { const f32x4 xv = *(const f32x4*)(xr + 4 * lane + 256 * j), ov = *(const f32x4*)(orow + 4 * lane + 256 * j), gv = *(const f32x4*)(A.g_post + 4 * lane + 256 * j);
;                     *(f32x4*)(yr + 4 * lane + 256 * j) = xv + ov * rstd * gv; }
;             }
.LBB0_1152:
	s_or_b64 exec, exec, s[4:5]
	s_ashr_i32 s3, s2, 31
	v_readlane_b32 s8, v253, 7
	s_lshl_b64 s[2:3], s[2:3], 12
	v_readlane_b32 s10, v253, 9
	v_readlane_b32 s11, v253, 10
	s_add_u32 s2, s10, s2
	s_addc_u32 s3, s11, s3
	s_lshl_b64 s[0:1], s[0:1], 12
	s_add_u32 s4, s94, s0
	s_addc_u32 s5, s95, s1
	v_lshlrev_b32_e32 v2, 4, v2
	v_lshl_add_u64 v[16:17], s[4:5], 0, v[2:3]
	s_mov_b32 s4, 0xf400000
	v_add_co_u32_e32 v18, vcc, s4, v16
	s_nop 1
	v_addc_co_u32_e32 v19, vcc, 0, v17, vcc
	global_load_dwordx4 v[4:7], v[18:19], off
	global_load_dwordx4 v[8:11], v2, s[2:3]
	global_load_dwordx4 v[12:15], v2, s[88:89]
	global_load_dwordx4 v[24:27], v[18:19], off offset:1024
	global_load_dwordx4 v[28:31], v2, s[2:3] offset:1024
	global_load_dwordx4 v[32:35], v2, s[88:89] offset:1024
	global_load_dwordx4 v[36:39], v[18:19], off offset:2048
	global_load_dwordx4 v[40:43], v2, s[2:3] offset:2048
	global_load_dwordx4 v[44:47], v2, s[88:89] offset:2048
	global_load_dwordx4 v[48:51], v[18:19], off offset:3072
	global_load_dwordx4 v[52:55], v2, s[2:3] offset:3072
	global_load_dwordx4 v[56:59], v2, s[88:89] offset:3072
	s_waitcnt vmcnt(12)
	v_add_f32_dpp v1, v1, v1 quad_perm:[1,0,3,2] row_mask:0xf bank_mask:0xf bound_ctrl:1
	s_nop 1
	v_add_f32_dpp v1, v1, v1 quad_perm:[2,3,0,1] row_mask:0xf bank_mask:0xf bound_ctrl:1
	v_mov_b32_e32 v3, 0x358637bd
	s_mov_b32 s4, 0xf800000
	v_add_f32_dpp v1, v1, v1 row_half_mirror row_mask:0xf bank_mask:0xf bound_ctrl:1
	v_mov_b32_e32 v18, 0x260
	v_readlane_b32 s9, v253, 8
	v_add_f32_dpp v1, v1, v1 row_mirror row_mask:0xf bank_mask:0xf bound_ctrl:1
	v_mov_b32_e32 v19, v1
	s_nop 1
	v_permlane16_swap_b32_e32 v1, v19
	v_add_f32_e32 v1, v1, v19
	v_mov_b32_e32 v19, v1
	s_nop 1
	v_permlane32_swap_b32_e32 v1, v19
	v_add_f32_e32 v1, v1, v19
	v_fmac_f32_e32 v3, 0x3a800000, v1
	v_mul_f32_e32 v1, 0x4f800000, v3
	v_cmp_gt_f32_e32 vcc, s4, v3
	s_add_u32 s4, s92, s0
	s_addc_u32 s5, s93, s1
	v_cndmask_b32_e32 v1, v3, v1, vcc
	v_sqrt_f32_e32 v3, v1
	s_mov_b64 s[8:9], 0xf400000
	v_lshl_add_u64 v[16:17], v[16:17], 0, s[8:9]
	v_readlane_b32 s12, v253, 11
	v_add_u32_e32 v19, -1, v3
	v_add_u32_e32 v20, 1, v3
	v_fma_f32 v21, -v19, v3, v1
	v_fma_f32 v22, -v20, v3, v1
	v_cmp_ge_f32_e64 s[0:1], 0, v21
	v_readlane_b32 s13, v253, 12
	v_readlane_b32 s14, v253, 13
	v_cndmask_b32_e64 v3, v3, v19, s[0:1]
	v_cmp_lt_f32_e64 s[0:1], 0, v22
	v_readlane_b32 s15, v253, 14
	v_readlane_b32 s16, v253, 15
	v_cndmask_b32_e64 v3, v3, v20, s[0:1]
	v_mul_f32_e32 v19, 0x37800000, v3
	v_cndmask_b32_e32 v3, v3, v19, vcc
	v_cmp_class_f32_e32 vcc, v1, v18
	v_readlane_b32 s17, v253, 16
	v_readlane_b32 s18, v253, 17
	v_cndmask_b32_e32 v1, v3, v1, vcc
	v_div_scale_f32 v3, s[0:1], v1, v1, 1.0
	v_rcp_f32_e32 v18, v3
	v_div_scale_f32 v19, vcc, 1.0, v1, 1.0
	v_readlane_b32 s19, v253, 18
	v_fma_f32 v20, -v3, v18, 1.0
	v_fmac_f32_e32 v18, v20, v18
	v_mul_f32_e32 v20, v19, v18
	v_fma_f32 v21, -v3, v20, v19
	v_fmac_f32_e32 v20, v21, v18
	v_fma_f32 v3, -v3, v20, v19
	v_div_fmas_f32 v3, v3, v18, v20
	v_div_fixup_f32 v18, v3, v1, 1.0
	v_readlane_b32 s20, v253, 19
	v_readlane_b32 s21, v253, 20
	v_readlane_b32 s22, v253, 21
	v_readlane_b32 s23, v253, 22
	s_waitcnt vmcnt(9)
	v_pk_mul_f32 v[4:5], v[18:19], v[4:5] op_sel_hi:[0,1]
	v_pk_mul_f32 v[6:7], v[18:19], v[6:7] op_sel_hi:[0,1]
	v_pk_fma_f32 v[6:7], v[6:7], v[14:15], v[10:11]
	v_pk_fma_f32 v[4:5], v[4:5], v[12:13], v[8:9]
	s_waitcnt vmcnt(6)
	v_pk_mul_f32 v[26:27], v[18:19], v[26:27] op_sel_hi:[0,1]
	v_pk_mul_f32 v[24:25], v[18:19], v[24:25] op_sel_hi:[0,1]
	v_pk_fma_f32 v[24:25], v[24:25], v[32:33], v[28:29]
	v_pk_fma_f32 v[26:27], v[26:27], v[34:35], v[30:31]
	s_waitcnt vmcnt(3)
	v_pk_mul_f32 v[38:39], v[18:19], v[38:39] op_sel_hi:[0,1]
	v_pk_mul_f32 v[36:37], v[18:19], v[36:37] op_sel_hi:[0,1]
	v_pk_fma_f32 v[36:37], v[36:37], v[44:45], v[40:41]
	v_pk_fma_f32 v[38:39], v[38:39], v[46:47], v[42:43]
	s_waitcnt vmcnt(0)
	v_pk_mul_f32 v[50:51], v[18:19], v[50:51] op_sel_hi:[0,1]
	v_pk_mul_f32 v[48:49], v[18:19], v[48:49] op_sel_hi:[0,1]
	v_pk_fma_f32 v[48:49], v[48:49], v[56:57], v[52:53]
	v_pk_fma_f32 v[50:51], v[50:51], v[58:59], v[54:55]
	global_store_dwordx4 v2, v[4:7], s[4:5]
	global_store_dwordx4 v2, v[24:27], s[4:5] offset:1024
	global_store_dwordx4 v2, v[36:39], s[4:5] offset:2048
	global_store_dwordx4 v2, v[48:51], s[4:5] offset:3072

;     __device__ __forceinline__ void fused(f32x4 (&acc)[2][2][4][2], const Unit& u, int wr, int wc, int fr, int fq, PG8_LAS unsigned char* lds, int wid, int lane) const {
;     ...
;         const float qnan = __builtin_nanf("");
;         const float* xb = (u.pm < 64) ? (x_p + (size_t)u.pm * BM * 1024) : (x_s + (size_t)(u.pm - 64) * BM * 1024);
;         float* ob = out + (size_t)u.pm * BM * 1024;
; #pragma unroll
;         for (int ai = 0; ai < 2; ++ai)
; #pragma unroll
;             for (int m = 0; m < 4; ++m) { const int r = ai * HALF + wr * 64 + m * 16 + fr; const float rs = S[r]; const size_t off = (size_t)r * 1024 + col0;
; #pragma unroll
;                 for (int bj = 0; bj < 2; ++bj)
; #pragma unroll
;                     for (int n = 0; n < 2; ++n) { const f32x4 xv = *(const f32x4*)(xb + off + bj * HALF + n * 16); f32x4 o = xv + acc[ai][bj][m][n] * rs * gv[bj][n];
;                         if (bad) o = (f32x4){qnan, qnan, qnan, qnan}; *(f32x4*)(ob + off + bj * HALF + n * 16) = o; }
;                 if (m & 1) asm volatile("" ::: "memory"); }
.LBB0_1203:
	v_ashrrev_i32_e32 v147, 31, v146
	v_lshlrev_b64 v[0:1], 12, v[146:147]
	v_or_b32_e32 v0, v0, v150
	v_lshl_add_u64 v[156:157], s[0:1], 0, v[0:1]
	global_load_dwordx4 v[152:155], v[156:157], off
	v_lshl_add_u32 v147, v146, 2, 0
	v_add_u32_e32 v148, 0x2000, v147
	ds_read2_b32 v[158:159], v148 offset1:16
	s_add_u32 s2, s92, s2
	v_mov_b32_e32 v147, 0x7fc00000
	s_addc_u32 s3, s93, s3
	s_waitcnt lgkmcnt(0)
	v_cmp_eq_u32_e32 vcc, 0, v149
	v_pk_mul_f32 v[130:131], v[130:131], v[158:159] op_sel_hi:[1,0]
	v_pk_mul_f32 v[132:133], v[132:133], v[158:159] op_sel_hi:[1,0]
	v_lshl_add_u64 v[160:161], s[2:3], 0, v[0:1]
	v_pk_mul_f32 v[122:123], v[122:123], v[158:159] op_sel_hi:[1,0]
	v_pk_mul_f32 v[124:125], v[124:125], v[158:159] op_sel_hi:[1,0]
	v_pk_mul_f32 v[118:119], v[118:119], v[158:159] op_sel_hi:[1,0]
	v_pk_mul_f32 v[120:121], v[120:121], v[158:159] op_sel_hi:[1,0]
	v_pk_mul_f32 v[110:111], v[110:111], v[158:159] op_sel_hi:[1,0]
	v_pk_mul_f32 v[112:113], v[112:113], v[158:159] op_sel_hi:[1,0]
	s_mov_b64 s[4:5], 0x80000
	s_waitcnt vmcnt(0)
	v_pk_fma_f32 v[132:133], v[144:145], v[132:133], v[154:155]
	v_pk_fma_f32 v[130:131], v[142:143], v[130:131], v[152:153]
	v_cndmask_b32_e32 v133, v147, v133, vcc
	v_cndmask_b32_e32 v131, v147, v131, vcc
	v_cndmask_b32_e32 v130, v147, v130, vcc
	v_cndmask_b32_e32 v132, v147, v132, vcc
	global_store_dwordx4 v[160:161], v[130:133], off
	global_load_dwordx4 v[130:133], v[156:157], off offset:64
	s_waitcnt vmcnt(0)
	v_pk_fma_f32 v[124:125], v[140:141], v[124:125], v[132:133]
	v_pk_fma_f32 v[122:123], v[138:139], v[122:123], v[130:131]
	v_cndmask_b32_e32 v125, v147, v125, vcc
	v_cndmask_b32_e32 v123, v147, v123, vcc
	v_cndmask_b32_e32 v122, v147, v122, vcc
	v_cndmask_b32_e32 v124, v147, v124, vcc
	global_store_dwordx4 v[160:161], v[122:125], off offset:64
	global_load_dwordx4 v[122:125], v[156:157], off offset:512
	s_waitcnt vmcnt(0)
	v_pk_fma_f32 v[120:121], v[136:137], v[120:121], v[124:125]
	v_pk_fma_f32 v[118:119], v[134:135], v[118:119], v[122:123]
	v_cndmask_b32_e32 v121, v147, v121, vcc
	v_cndmask_b32_e32 v119, v147, v119, vcc
	v_cndmask_b32_e32 v118, v147, v118, vcc
	v_cndmask_b32_e32 v120, v147, v120, vcc
	global_store_dwordx4 v[160:161], v[118:121], off offset:512
	global_load_dwordx4 v[118:121], v[156:157], off offset:576
	v_or_b32_e32 v122, 16, v146
	v_ashrrev_i32_e32 v123, 31, v122
	v_lshlrev_b64 v[122:123], 12, v[122:123]
	v_or_b32_e32 v122, v122, v150
	v_lshl_add_u64 v[124:125], s[0:1], 0, v[122:123]
	s_waitcnt vmcnt(0)
	v_pk_fma_f32 v[112:113], v[128:129], v[112:113], v[120:121]
	v_pk_fma_f32 v[110:111], v[126:127], v[110:111], v[118:119]
	v_cndmask_b32_e32 v113, v147, v113, vcc
	v_cndmask_b32_e32 v111, v147, v111, vcc
	v_cndmask_b32_e32 v110, v147, v110, vcc
	v_cndmask_b32_e32 v112, v147, v112, vcc
	global_store_dwordx4 v[160:161], v[110:113], off offset:576
	global_load_dwordx4 v[110:113], v[124:125], off
	v_mov_b32_e32 v120, v159
	v_pk_mul_f32 v[114:115], v[114:115], v[120:121] op_sel_hi:[1,0]
	v_pk_mul_f32 v[116:117], v[116:117], v[120:121] op_sel_hi:[1,0]
	v_lshl_add_u64 v[118:119], s[2:3], 0, v[122:123]
	v_pk_mul_f32 v[106:107], v[106:107], v[120:121] op_sel_hi:[1,0]
	v_pk_mul_f32 v[108:109], v[108:109], v[120:121] op_sel_hi:[1,0]
	v_pk_mul_f32 v[102:103], v[102:103], v[120:121] op_sel_hi:[1,0]
	v_pk_mul_f32 v[104:105], v[104:105], v[120:121] op_sel_hi:[1,0]
	v_pk_mul_f32 v[94:95], v[94:95], v[120:121] op_sel_hi:[1,0]
	v_pk_mul_f32 v[96:97], v[96:97], v[120:121] op_sel_hi:[1,0]
	s_waitcnt vmcnt(0)
	v_pk_fma_f32 v[112:113], v[144:145], v[116:117], v[112:113]
	v_pk_fma_f32 v[110:111], v[142:143], v[114:115], v[110:111]
	v_cndmask_b32_e32 v113, v147, v113, vcc
	v_cndmask_b32_e32 v112, v147, v112, vcc
	v_cndmask_b32_e32 v111, v147, v111, vcc
	v_cndmask_b32_e32 v110, v147, v110, vcc
	global_store_dwordx4 v[118:119], v[110:113], off
	global_load_dwordx4 v[110:113], v[124:125], off offset:64
	s_waitcnt vmcnt(0)
	v_pk_fma_f32 v[108:109], v[140:141], v[108:109], v[112:113]
	v_pk_fma_f32 v[106:107], v[138:139], v[106:107], v[110:111]
	v_cndmask_b32_e32 v109, v147, v109, vcc
	v_cndmask_b32_e32 v108, v147, v108, vcc
	v_cndmask_b32_e32 v107, v147, v107, vcc
	v_cndmask_b32_e32 v106, v147, v106, vcc
	global_store_dwordx4 v[118:119], v[106:109], off offset:64
	global_load_dwordx4 v[106:109], v[124:125], off offset:512
	s_waitcnt vmcnt(0)
	v_pk_fma_f32 v[104:105], v[136:137], v[104:105], v[108:109]
	v_pk_fma_f32 v[102:103], v[134:135], v[102:103], v[106:107]
	v_cndmask_b32_e32 v105, v147, v105, vcc
	v_cndmask_b32_e32 v104, v147, v104, vcc
	v_cndmask_b32_e32 v103, v147, v103, vcc
	v_cndmask_b32_e32 v102, v147, v102, vcc
	global_store_dwordx4 v[118:119], v[102:105], off offset:512
	global_load_dwordx4 v[102:105], v[124:125], off offset:576
	v_or_b32_e32 v106, 32, v146
	v_ashrrev_i32_e32 v107, 31, v106
	v_lshlrev_b64 v[106:107], 12, v[106:107]
	v_or_b32_e32 v106, v106, v150
	v_lshl_add_u64 v[108:109], s[0:1], 0, v[106:107]
	s_waitcnt vmcnt(0)
	v_pk_fma_f32 v[96:97], v[128:129], v[96:97], v[104:105]
	v_pk_fma_f32 v[94:95], v[126:127], v[94:95], v[102:103]
	v_cndmask_b32_e32 v97, v147, v97, vcc
	v_cndmask_b32_e32 v96, v147, v96, vcc
	v_cndmask_b32_e32 v95, v147, v95, vcc
	v_cndmask_b32_e32 v94, v147, v94, vcc
	global_store_dwordx4 v[118:119], v[94:97], off offset:576
	global_load_dwordx4 v[94:97], v[108:109], off
	ds_read2_b32 v[102:103], v148 offset0:32 offset1:48
	v_lshl_add_u64 v[104:105], s[2:3], 0, v[106:107]
	s_waitcnt lgkmcnt(0)
;     __device__ __forceinline__ void fused(f32x4 (&acc)[2][2][4][2], const Unit& u, int wr, int wc, int fr, int fq, PG8_LAS unsigned char* lds, int wid, int lane) const {
;     ...
;         const float qnan = __builtin_nanf("");
;         const float* xb = (u.pm < 64) ? (x_p + (size_t)u.pm * BM * 1024) : (x_s + (size_t)(u.pm - 64) * BM * 1024);
;         float* ob = out + (size_t)u.pm * BM * 1024;
; #pragma unroll
;         for (int ai = 0; ai < 2; ++ai)
; #pragma unroll
;             for (int m = 0; m < 4; ++m) { const int r = ai * HALF + wr * 64 + m * 16 + fr; const float rs = S[r]; const size_t off = (size_t)r * 1024 + col0;
; #pragma unroll
;                 for (int bj = 0; bj < 2; ++bj)
; #pragma unroll
;                     for (int n = 0; n < 2; ++n) { const f32x4 xv = *(const f32x4*)(xb + off + bj * HALF + n * 16); f32x4 o = xv + acc[ai][bj][m][n] * rs * gv[bj][n];
;                         if (bad) o = (f32x4){qnan, qnan, qnan, qnan}; *(f32x4*)(ob + off + bj * HALF + n * 16) = o; }
;                 if (m & 1) asm volatile("" ::: "memory"); }
	v_pk_mul_f32 v[98:99], v[98:99], v[102:103] op_sel_hi:[1,0]
	v_pk_mul_f32 v[100:101], v[100:101], v[102:103] op_sel_hi:[1,0]
	v_pk_mul_f32 v[90:91], v[90:91], v[102:103] op_sel_hi:[1,0]
	v_pk_mul_f32 v[92:93], v[92:93], v[102:103] op_sel_hi:[1,0]
	v_pk_mul_f32 v[86:87], v[86:87], v[102:103] op_sel_hi:[1,0]
	v_pk_mul_f32 v[88:89], v[88:89], v[102:103] op_sel_hi:[1,0]
	v_pk_mul_f32 v[78:79], v[78:79], v[102:103] op_sel_hi:[1,0]
	v_pk_mul_f32 v[80:81], v[80:81], v[102:103] op_sel_hi:[1,0]
	s_waitcnt vmcnt(0)
	v_pk_fma_f32 v[96:97], v[144:145], v[100:101], v[96:97]
	v_pk_fma_f32 v[94:95], v[142:143], v[98:99], v[94:95]
	v_cndmask_b32_e32 v97, v147, v97, vcc
	v_cndmask_b32_e32 v96, v147, v96, vcc
	v_cndmask_b32_e32 v95, v147, v95, vcc
	v_cndmask_b32_e32 v94, v147, v94, vcc
	global_store_dwordx4 v[104:105], v[94:97], off
	global_load_dwordx4 v[94:97], v[108:109], off offset:64
	s_waitcnt vmcnt(0)
	v_pk_fma_f32 v[92:93], v[140:141], v[92:93], v[96:97]
	v_pk_fma_f32 v[90:91], v[138:139], v[90:91], v[94:95]
	v_cndmask_b32_e32 v93, v147, v93, vcc
	v_cndmask_b32_e32 v92, v147, v92, vcc
	v_cndmask_b32_e32 v91, v147, v91, vcc
	v_cndmask_b32_e32 v90, v147, v90, vcc
	global_store_dwordx4 v[104:105], v[90:93], off offset:64
	global_load_dwordx4 v[90:93], v[108:109], off offset:512
	s_waitcnt vmcnt(0)
	v_pk_fma_f32 v[88:89], v[136:137], v[88:89], v[92:93]
	v_pk_fma_f32 v[86:87], v[134:135], v[86:87], v[90:91]
	v_cndmask_b32_e32 v89, v147, v89, vcc
	v_cndmask_b32_e32 v88, v147, v88, vcc
	v_cndmask_b32_e32 v87, v147, v87, vcc
	v_cndmask_b32_e32 v86, v147, v86, vcc
	global_store_dwordx4 v[104:105], v[86:89], off offset:512
	global_load_dwordx4 v[86:89], v[108:109], off offset:576
	v_or_b32_e32 v90, 48, v146
	v_ashrrev_i32_e32 v91, 31, v90
	v_lshlrev_b64 v[90:91], 12, v[90:91]
	v_or_b32_e32 v90, v90, v150
	v_lshl_add_u64 v[92:93], s[0:1], 0, v[90:91]
	s_waitcnt vmcnt(0)
	v_pk_fma_f32 v[80:81], v[128:129], v[80:81], v[88:89]
	v_pk_fma_f32 v[78:79], v[126:127], v[78:79], v[86:87]
	v_cndmask_b32_e32 v81, v147, v81, vcc
	v_cndmask_b32_e32 v80, v147, v80, vcc
	v_cndmask_b32_e32 v79, v147, v79, vcc
	v_cndmask_b32_e32 v78, v147, v78, vcc
	global_store_dwordx4 v[104:105], v[78:81], off offset:576
	global_load_dwordx4 v[78:81], v[92:93], off
	v_mov_b32_e32 v88, v103
	v_pk_mul_f32 v[82:83], v[82:83], v[88:89] op_sel_hi:[1,0]
	v_pk_mul_f32 v[84:85], v[84:85], v[88:89] op_sel_hi:[1,0]
	v_lshl_add_u64 v[86:87], s[2:3], 0, v[90:91]
	v_pk_mul_f32 v[74:75], v[74:75], v[88:89] op_sel_hi:[1,0]
	v_pk_mul_f32 v[76:77], v[76:77], v[88:89] op_sel_hi:[1,0]
	v_pk_mul_f32 v[70:71], v[70:71], v[88:89] op_sel_hi:[1,0]
	v_pk_mul_f32 v[72:73], v[72:73], v[88:89] op_sel_hi:[1,0]
	v_pk_mul_f32 v[66:67], v[66:67], v[88:89] op_sel_hi:[1,0]
	v_pk_mul_f32 v[68:69], v[68:69], v[88:89] op_sel_hi:[1,0]
	s_waitcnt vmcnt(0)
	v_pk_fma_f32 v[80:81], v[144:145], v[84:85], v[80:81]
	v_pk_fma_f32 v[78:79], v[142:143], v[82:83], v[78:79]
	v_cndmask_b32_e32 v81, v147, v81, vcc
	v_cndmask_b32_e32 v80, v147, v80, vcc
	v_cndmask_b32_e32 v79, v147, v79, vcc
	v_cndmask_b32_e32 v78, v147, v78, vcc
	global_store_dwordx4 v[86:87], v[78:81], off
	global_load_dwordx4 v[78:81], v[92:93], off offset:64
	s_waitcnt vmcnt(0)
	v_pk_fma_f32 v[76:77], v[140:141], v[76:77], v[80:81]
	v_pk_fma_f32 v[74:75], v[138:139], v[74:75], v[78:79]
	v_cndmask_b32_e32 v77, v147, v77, vcc
	v_cndmask_b32_e32 v76, v147, v76, vcc
	v_cndmask_b32_e32 v75, v147, v75, vcc
	v_cndmask_b32_e32 v74, v147, v74, vcc
	global_store_dwordx4 v[86:87], v[74:77], off offset:64
	global_load_dwordx4 v[74:77], v[92:93], off offset:512
	s_waitcnt vmcnt(0)
	v_pk_fma_f32 v[72:73], v[136:137], v[72:73], v[76:77]
	v_pk_fma_f32 v[70:71], v[134:135], v[70:71], v[74:75]
	v_cndmask_b32_e32 v73, v147, v73, vcc
	v_cndmask_b32_e32 v72, v147, v72, vcc
	v_cndmask_b32_e32 v71, v147, v71, vcc
	v_cndmask_b32_e32 v70, v147, v70, vcc
	global_store_dwordx4 v[86:87], v[70:73], off offset:512
	global_load_dwordx4 v[70:73], v[92:93], off offset:576
	v_lshl_add_u64 v[74:75], v[0:1], 0, s[4:5]
	v_lshl_add_u64 v[76:77], s[0:1], 0, v[74:75]
	s_mov_b64 s[4:5], 0x90000
	s_waitcnt vmcnt(0)
	v_pk_fma_f32 v[68:69], v[128:129], v[68:69], v[72:73]
	v_pk_fma_f32 v[66:67], v[126:127], v[66:67], v[70:71]
	v_cndmask_b32_e32 v69, v147, v69, vcc
	v_cndmask_b32_e32 v68, v147, v68, vcc
	v_cndmask_b32_e32 v67, v147, v67, vcc
	v_cndmask_b32_e32 v66, v147, v66, vcc
	global_store_dwordx4 v[86:87], v[66:69], off offset:576
	global_load_dwordx4 v[66:69], v[76:77], off
	ds_read2_b32 v[70:71], v148 offset0:128 offset1:144
	v_lshl_add_u64 v[72:73], s[2:3], 0, v[74:75]
	s_waitcnt lgkmcnt(0)
	v_pk_mul_f32 v[64:65], v[64:65], v[70:71] op_sel_hi:[1,0]
	v_pk_mul_f32 v[62:63], v[62:63], v[70:71] op_sel_hi:[1,0]
	v_pk_mul_f32 v[58:59], v[58:59], v[70:71] op_sel_hi:[1,0]
	v_pk_mul_f32 v[60:61], v[60:61], v[70:71] op_sel_hi:[1,0]
	v_pk_mul_f32 v[54:55], v[54:55], v[70:71] op_sel_hi:[1,0]
	v_pk_mul_f32 v[56:57], v[56:57], v[70:71] op_sel_hi:[1,0]
	v_pk_mul_f32 v[46:47], v[46:47], v[70:71] op_sel_hi:[1,0]
	v_pk_mul_f32 v[48:49], v[48:49], v[70:71] op_sel_hi:[1,0]
	s_waitcnt vmcnt(0)
	v_pk_fma_f32 v[62:63], v[142:143], v[62:63], v[66:67]
	v_pk_fma_f32 v[64:65], v[144:145], v[64:65], v[68:69]
	v_cndmask_b32_e32 v63, v147, v63, vcc
	v_cndmask_b32_e32 v65, v147, v65, vcc
	v_cndmask_b32_e32 v64, v147, v64, vcc
	v_cndmask_b32_e32 v62, v147, v62, vcc
	global_store_dwordx4 v[72:73], v[62:65], off
	global_load_dwordx4 v[62:65], v[76:77], off offset:64
	s_waitcnt vmcnt(0)
;     __device__ __forceinline__ void fused(f32x4 (&acc)[2][2][4][2], const Unit& u, int wr, int wc, int fr, int fq, PG8_LAS unsigned char* lds, int wid, int lane) const {
;     ...
;         const float qnan = __builtin_nanf("");
;         const float* xb = (u.pm < 64) ? (x_p + (size_t)u.pm * BM * 1024) : (x_s + (size_t)(u.pm - 64) * BM * 1024);
;         float* ob = out + (size_t)u.pm * BM * 1024;
; #pragma unroll
;         for (int ai = 0; ai < 2; ++ai)
; #pragma unroll
;             for (int m = 0; m < 4; ++m) { const int r = ai * HALF + wr * 64 + m * 16 + fr; const float rs = S[r]; const size_t off = (size_t)r * 1024 + col0;
; #pragma unroll
;                 for (int bj = 0; bj < 2; ++bj)
; #pragma unroll
;                     for (int n = 0; n < 2; ++n) { const f32x4 xv = *(const f32x4*)(xb + off + bj * HALF + n * 16); f32x4 o = xv + acc[ai][bj][m][n] * rs * gv[bj][n];
;                         if (bad) o = (f32x4){qnan, qnan, qnan, qnan}; *(f32x4*)(ob + off + bj * HALF + n * 16) = o; }
;                 if (m & 1) asm volatile("" ::: "memory"); }
	v_pk_fma_f32 v[60:61], v[140:141], v[60:61], v[64:65]
	v_pk_fma_f32 v[58:59], v[138:139], v[58:59], v[62:63]
	v_cndmask_b32_e32 v61, v147, v61, vcc
	v_cndmask_b32_e32 v59, v147, v59, vcc
	v_cndmask_b32_e32 v58, v147, v58, vcc
	v_cndmask_b32_e32 v60, v147, v60, vcc
	global_store_dwordx4 v[72:73], v[58:61], off offset:64
	global_load_dwordx4 v[58:61], v[76:77], off offset:512
	s_waitcnt vmcnt(0)
	v_pk_fma_f32 v[56:57], v[136:137], v[56:57], v[60:61]
	v_pk_fma_f32 v[54:55], v[134:135], v[54:55], v[58:59]
	v_cndmask_b32_e32 v57, v147, v57, vcc
	v_cndmask_b32_e32 v55, v147, v55, vcc
	v_cndmask_b32_e32 v54, v147, v54, vcc
	v_cndmask_b32_e32 v56, v147, v56, vcc
	global_store_dwordx4 v[72:73], v[54:57], off offset:512
	global_load_dwordx4 v[54:57], v[76:77], off offset:576
	v_lshl_add_u64 v[58:59], v[0:1], 0, s[4:5]
	v_lshl_add_u64 v[60:61], s[0:1], 0, v[58:59]
	s_mov_b64 s[4:5], 0xa0000
	s_waitcnt vmcnt(0)
	v_pk_fma_f32 v[48:49], v[128:129], v[48:49], v[56:57]
	v_pk_fma_f32 v[46:47], v[126:127], v[46:47], v[54:55]
	v_cndmask_b32_e32 v49, v147, v49, vcc
	v_cndmask_b32_e32 v47, v147, v47, vcc
	v_cndmask_b32_e32 v46, v147, v46, vcc
	v_cndmask_b32_e32 v48, v147, v48, vcc
	global_store_dwordx4 v[72:73], v[46:49], off offset:576
	global_load_dwordx4 v[46:49], v[60:61], off
	v_mov_b32_e32 v56, v71
	v_pk_mul_f32 v[50:51], v[50:51], v[56:57] op_sel_hi:[1,0]
	v_pk_mul_f32 v[52:53], v[52:53], v[56:57] op_sel_hi:[1,0]
	v_lshl_add_u64 v[54:55], s[2:3], 0, v[58:59]
	v_pk_mul_f32 v[42:43], v[42:43], v[56:57] op_sel_hi:[1,0]
	v_pk_mul_f32 v[44:45], v[44:45], v[56:57] op_sel_hi:[1,0]
	v_pk_mul_f32 v[38:39], v[38:39], v[56:57] op_sel_hi:[1,0]
	v_pk_mul_f32 v[40:41], v[40:41], v[56:57] op_sel_hi:[1,0]
	v_pk_mul_f32 v[30:31], v[30:31], v[56:57] op_sel_hi:[1,0]
	v_pk_mul_f32 v[32:33], v[32:33], v[56:57] op_sel_hi:[1,0]
	s_waitcnt vmcnt(0)
	v_pk_fma_f32 v[48:49], v[144:145], v[52:53], v[48:49]
	v_pk_fma_f32 v[46:47], v[142:143], v[50:51], v[46:47]
	v_cndmask_b32_e32 v49, v147, v49, vcc
	v_cndmask_b32_e32 v47, v147, v47, vcc
	v_cndmask_b32_e32 v46, v147, v46, vcc
	v_cndmask_b32_e32 v48, v147, v48, vcc
	global_store_dwordx4 v[54:55], v[46:49], off
	global_load_dwordx4 v[46:49], v[60:61], off offset:64
	s_waitcnt vmcnt(0)
	v_pk_fma_f32 v[44:45], v[140:141], v[44:45], v[48:49]
	v_pk_fma_f32 v[42:43], v[138:139], v[42:43], v[46:47]
	v_cndmask_b32_e32 v45, v147, v45, vcc
	v_cndmask_b32_e32 v43, v147, v43, vcc
	v_cndmask_b32_e32 v42, v147, v42, vcc
	v_cndmask_b32_e32 v44, v147, v44, vcc
	global_store_dwordx4 v[54:55], v[42:45], off offset:64
	global_load_dwordx4 v[42:45], v[60:61], off offset:512
	s_waitcnt vmcnt(0)
	v_pk_fma_f32 v[40:41], v[136:137], v[40:41], v[44:45]
	v_pk_fma_f32 v[38:39], v[134:135], v[38:39], v[42:43]
	v_cndmask_b32_e32 v41, v147, v41, vcc
	v_cndmask_b32_e32 v39, v147, v39, vcc
	v_cndmask_b32_e32 v38, v147, v38, vcc
	v_cndmask_b32_e32 v40, v147, v40, vcc
	global_store_dwordx4 v[54:55], v[38:41], off offset:512
	global_load_dwordx4 v[38:41], v[60:61], off offset:576
	v_lshl_add_u64 v[42:43], v[0:1], 0, s[4:5]
	v_lshl_add_u64 v[44:45], s[0:1], 0, v[42:43]
	s_mov_b64 s[4:5], 0xb0000
	v_lshl_add_u64 v[0:1], v[0:1], 0, s[4:5]
	s_waitcnt vmcnt(0)
	v_pk_fma_f32 v[32:33], v[128:129], v[32:33], v[40:41]
	v_pk_fma_f32 v[30:31], v[126:127], v[30:31], v[38:39]
	v_cndmask_b32_e32 v33, v147, v33, vcc
	v_cndmask_b32_e32 v31, v147, v31, vcc
	v_cndmask_b32_e32 v30, v147, v30, vcc
	v_cndmask_b32_e32 v32, v147, v32, vcc
	global_store_dwordx4 v[54:55], v[30:33], off offset:576
	global_load_dwordx4 v[30:33], v[44:45], off
	ds_read2_b32 v[38:39], v148 offset0:160 offset1:176
	v_lshl_add_u64 v[40:41], s[2:3], 0, v[42:43]
	s_waitcnt lgkmcnt(0)
;     __device__ __forceinline__ void fused(f32x4 (&acc)[2][2][4][2], const Unit& u, int wr, int wc, int fr, int fq, PG8_LAS unsigned char* lds, int wid, int lane) const {
;     ...
;         const float qnan = __builtin_nanf("");
;         const float* xb = (u.pm < 64) ? (x_p + (size_t)u.pm * BM * 1024) : (x_s + (size_t)(u.pm - 64) * BM * 1024);
;         float* ob = out + (size_t)u.pm * BM * 1024;
; #pragma unroll
;         for (int ai = 0; ai < 2; ++ai)
; #pragma unroll
;             for (int m = 0; m < 4; ++m) { const int r = ai * HALF + wr * 64 + m * 16 + fr; const float rs = S[r]; const size_t off = (size_t)r * 1024 + col0;
; #pragma unroll
;                 for (int bj = 0; bj < 2; ++bj)
; #pragma unroll
;                     for (int n = 0; n < 2; ++n) { const f32x4 xv = *(const f32x4*)(xb + off + bj * HALF + n * 16); f32x4 o = xv + acc[ai][bj][m][n] * rs * gv[bj][n];
;                         if (bad) o = (f32x4){qnan, qnan, qnan, qnan}; *(f32x4*)(ob + off + bj * HALF + n * 16) = o; }
;                 if (m & 1) asm volatile("" ::: "memory"); }
	v_pk_mul_f32 v[36:37], v[36:37], v[38:39] op_sel_hi:[1,0]
	v_pk_mul_f32 v[34:35], v[34:35], v[38:39] op_sel_hi:[1,0]
	v_pk_mul_f32 v[26:27], v[26:27], v[38:39] op_sel_hi:[1,0]
	v_pk_mul_f32 v[28:29], v[28:29], v[38:39] op_sel_hi:[1,0]
	v_pk_mul_f32 v[22:23], v[22:23], v[38:39] op_sel_hi:[1,0]
	v_pk_mul_f32 v[24:25], v[24:25], v[38:39] op_sel_hi:[1,0]
	v_pk_mul_f32 v[14:15], v[14:15], v[38:39] op_sel_hi:[1,0]
	v_pk_mul_f32 v[16:17], v[16:17], v[38:39] op_sel_hi:[1,0]
	s_waitcnt vmcnt(0)
	v_pk_fma_f32 v[30:31], v[142:143], v[34:35], v[30:31]
	v_pk_fma_f32 v[32:33], v[144:145], v[36:37], v[32:33]
	v_cndmask_b32_e32 v31, v147, v31, vcc
	v_cndmask_b32_e32 v33, v147, v33, vcc
	v_cndmask_b32_e32 v32, v147, v32, vcc
	v_cndmask_b32_e32 v30, v147, v30, vcc
	global_store_dwordx4 v[40:41], v[30:33], off
	global_load_dwordx4 v[30:33], v[44:45], off offset:64
	s_waitcnt vmcnt(0)
	v_pk_fma_f32 v[28:29], v[140:141], v[28:29], v[32:33]
	v_pk_fma_f32 v[26:27], v[138:139], v[26:27], v[30:31]
	v_cndmask_b32_e32 v29, v147, v29, vcc
	v_cndmask_b32_e32 v27, v147, v27, vcc
	v_cndmask_b32_e32 v26, v147, v26, vcc
	v_cndmask_b32_e32 v28, v147, v28, vcc
	global_store_dwordx4 v[40:41], v[26:29], off offset:64
	global_load_dwordx4 v[26:29], v[44:45], off offset:512
	s_waitcnt vmcnt(0)
	v_pk_fma_f32 v[24:25], v[136:137], v[24:25], v[28:29]
	v_pk_fma_f32 v[22:23], v[134:135], v[22:23], v[26:27]
	v_cndmask_b32_e32 v25, v147, v25, vcc
	v_cndmask_b32_e32 v23, v147, v23, vcc
	v_cndmask_b32_e32 v22, v147, v22, vcc
	v_cndmask_b32_e32 v24, v147, v24, vcc
	global_store_dwordx4 v[40:41], v[22:25], off offset:512
	global_load_dwordx4 v[22:25], v[44:45], off offset:576
	v_lshl_add_u64 v[26:27], s[0:1], 0, v[0:1]
	s_waitcnt vmcnt(0)
	v_pk_fma_f32 v[16:17], v[128:129], v[16:17], v[24:25]
	v_pk_fma_f32 v[14:15], v[126:127], v[14:15], v[22:23]
	v_cndmask_b32_e32 v17, v147, v17, vcc
	v_cndmask_b32_e32 v15, v147, v15, vcc
	v_cndmask_b32_e32 v14, v147, v14, vcc
	v_cndmask_b32_e32 v16, v147, v16, vcc
	global_store_dwordx4 v[40:41], v[14:17], off offset:576
	global_load_dwordx4 v[14:17], v[26:27], off
	v_lshl_add_u64 v[22:23], s[2:3], 0, v[0:1]
	v_mov_b32_e32 v0, v39
	v_pk_mul_f32 v[18:19], v[18:19], v[0:1] op_sel_hi:[1,0]
	v_pk_mul_f32 v[20:21], v[20:21], v[0:1] op_sel_hi:[1,0]
	v_pk_mul_f32 v[10:11], v[10:11], v[0:1] op_sel_hi:[1,0]
	v_pk_mul_f32 v[12:13], v[12:13], v[0:1] op_sel_hi:[1,0]
	v_pk_mul_f32 v[6:7], v[6:7], v[0:1] op_sel_hi:[1,0]
	v_pk_mul_f32 v[8:9], v[8:9], v[0:1] op_sel_hi:[1,0]
	v_pk_mul_f32 v[2:3], v[2:3], v[0:1] op_sel_hi:[1,0]
	v_pk_mul_f32 v[0:1], v[4:5], v[0:1] op_sel_hi:[1,0]
	s_waitcnt vmcnt(0)
	v_pk_fma_f32 v[16:17], v[144:145], v[20:21], v[16:17]
	v_pk_fma_f32 v[14:15], v[142:143], v[18:19], v[14:15]
	v_cndmask_b32_e32 v17, v147, v17, vcc
	v_cndmask_b32_e32 v15, v147, v15, vcc
	v_cndmask_b32_e32 v14, v147, v14, vcc
	v_cndmask_b32_e32 v16, v147, v16, vcc
	global_store_dwordx4 v[22:23], v[14:17], off
	global_load_dwordx4 v[14:17], v[26:27], off offset:64
	s_waitcnt vmcnt(0)
	v_pk_fma_f32 v[12:13], v[140:141], v[12:13], v[16:17]
	v_pk_fma_f32 v[10:11], v[138:139], v[10:11], v[14:15]
	v_cndmask_b32_e32 v13, v147, v13, vcc
	v_cndmask_b32_e32 v11, v147, v11, vcc
	v_cndmask_b32_e32 v10, v147, v10, vcc
	v_cndmask_b32_e32 v12, v147, v12, vcc
	global_store_dwordx4 v[22:23], v[10:13], off offset:64
	global_load_dwordx4 v[10:13], v[26:27], off offset:512
	s_waitcnt vmcnt(0)
	v_pk_fma_f32 v[8:9], v[136:137], v[8:9], v[12:13]
	v_pk_fma_f32 v[6:7], v[134:135], v[6:7], v[10:11]
	v_cndmask_b32_e32 v9, v147, v9, vcc
	v_cndmask_b32_e32 v7, v147, v7, vcc
	v_cndmask_b32_e32 v6, v147, v6, vcc
	v_cndmask_b32_e32 v8, v147, v8, vcc
	global_store_dwordx4 v[22:23], v[6:9], off offset:512
	global_load_dwordx4 v[6:9], v[26:27], off offset:576
	s_waitcnt vmcnt(0)
	v_pk_fma_f32 v[4:5], v[128:129], v[0:1], v[8:9]
	v_pk_fma_f32 v[0:1], v[126:127], v[2:3], v[6:7]
	v_cndmask_b32_e32 v3, v147, v5, vcc
	v_cndmask_b32_e32 v1, v147, v1, vcc
	v_cndmask_b32_e32 v0, v147, v0, vcc
	v_cndmask_b32_e32 v2, v147, v4, vcc
	global_store_dwordx4 v[22:23], v[0:3], off offset:576
	s_endpgm
